# gates GEMM tile order: two 6-column weight panels (on top of the GEMM-1 8-column panels)
# speedup vs baseline: 1.0137x; 1.0086x over previous
; DEV int bid_() { int b = blockIdx.x; asm volatile("" : "+s"(b)); return b; }
; __device__ void phase_gates(PRef p, int l, const bf16* H2, bf16* sA, bf16* sB) {
;     ...
;   for (int t = bid_() >> 3; t < 36 * 12; t += per_) {
;     int rt = xcd_ + 8 * (t / 12), ct = t % 12;
;     if (skip_rt(l, rt)) continue;
;     f32x16 acc[2][2];
;     zero_acc<2>(acc);
;     gemm_tile<2>(acc, H2 + (size_t)rt * 128 * 1024, 1024, p.WT2 + (size_t)ct * 128 * 1024, 1024, 1024, sA, sB);
.LBB0_869:
	s_mul_hi_i32 s0, s16, 0x2aaaaaab
	s_lshr_b32 s1, s0, 31
	s_ashr_i32 s0, s0, 1
	s_add_i32 s0, s0, s1
	s_movk_i32 s1, 0xd8
	s_cmp_lg_u64 s[6:7], 0
	s_cselect_b32 s1, 0xc0, s1
	s_cmp_ge_u32 s16, s1
	s_cselect_b32 s0, 6, 0
	s_cselect_b32 s1, s1, 0
	s_sub_u32 s1, s16, s1
	s_mul_i32 s10, s1, 0x2aab
	s_lshr_b32 s10, s10, 16
	s_mul_i32 s11, s10, 6
	s_sub_u32 s1, s1, s11
	s_add_u32 s0, s0, s1
	s_mov_b32 s1, s10
	s_mov_b32 s12, -1
	s_mov_b32 s13, 15
	s_cmp_eq_u64 s[6:7], 0
	s_cbranch_scc1 .Lbalg_clr0
	s_lshr_b32 s10, s17, 1
	s_mov_b32 s12, 0xf7fbfdfe
	s_cmp_eq_u32 s10, 1
	s_cselect_b32 s12, 0xdfeff7fb, s12
	s_cmp_eq_u32 s10, 2
	s_cselect_b32 s12, 0x7fbfdfef, s12
	s_cmp_eq_u32 s10, 3
	s_cselect_b32 s12, 0xfeff7fbf, s12
	s_cselect_b32 s13, 13, 15

; DEV int tid_() { int t = threadIdx.x; asm volatile("" : "+v"(t)); return t; }
; template <int NI, bool DEEP = true>
; DEV void gemm_tile(f32x16 (&acc)[2][NI], const bf16* __restrict__ A, int lda, const bf16* __restrict__ Bt, int ldb,
;                    int K, bf16* sA, bf16* sB) {
;   int tid = tid_(), lane = tid & 63, wave = tid >> 6;
;   int wm = wave >> 1, wn = wave & 1;
;   int lr = tid >> 3, lc = (tid & 7) * 8;
;   const bf16* Ap = A + (size_t)lr * lda + lc;
;   const bf16* Bp = Bt + (size_t)lr * ldb + lc;
;   u32x4 ra0[4], rb0[2 * NI], ra1[4], rb1[2 * NI];
; __device__ void phase_gates(PRef p, int l, const bf16* H2, bf16* sA, bf16* sB) {
;     ...
;     int rt = xcd_ + 8 * (t / 12), ct = t % 12;
;     if (skip_rt(l, rt)) continue;
;     f32x16 acc[2][2];
;     zero_acc<2>(acc);
;     gemm_tile<2>(acc, H2 + (size_t)rt * 128 * 1024, 1024, p.WT2 + (size_t)ct * 128 * 1024, 1024, 1024, sA, sB);
.Lbalg_nth:
	s_ff1_i32_b64 s1, s[12:13]
	s_lshl_b32 s1, s1, 3
	s_or_b32 s10, s1, s17
	s_mov_b32 s12, s0
	v_readlane_b32 s14, v245, 4
	v_readlane_b32 s15, v245, 5
	s_lshl_b32 s0, s10, 18
	s_add_u32 s98, s14, s0
	s_addc_u32 s99, s15, 0
	s_lshl_b32 s0, s12, 18
	s_waitcnt lgkmcnt(0)
	s_add_u32 s100, s4, s0
	s_addc_u32 s101, s5, 0
	v_and_b32_e32 v0, 63, v196
	v_lshrrev_b32_e32 v1, 6, v196
	v_lshrrev_b32_e32 v2, 3, v0
	v_readfirstlane_b32 s0, v1
	v_lshrrev_b32_e32 v78, 1, v2
	v_and_b32_e32 v79, 7, v0
	v_xor_b32_e32 v78, v79, v78
	v_lshlrev_b32_e32 v78, 4, v78
	v_lshl_or_b32 v68, v2, 11, v78
	v_xor_b32_e32 v69, 64, v68
	v_lshrrev_b32_e32 v78, 5, v0
	v_bfe_u32 v79, v0, 1, 3
	v_and_b32_e32 v2, 31, v0
	v_lshrrev_b32_e32 v0, 1, v1
	v_and_b32_e32 v1, 1, v1
	v_lshl_add_u32 v0, v0, 6, v2
	v_lshl_add_u32 v1, v1, 6, v2
	v_lshlrev_b32_e32 v0, 7, v0
	v_lshlrev_b32_e32 v1, 7, v1
	v_add_u32_e32 v1, 0x4000, v1
	v_add_u32_e32 v2, 0, v78
	v_xor_b32_e32 v2, v2, v79
	v_lshl_add_u32 v70, v2, 4, v0
	v_lshl_add_u32 v74, v2, 4, v1
	v_add_u32_e32 v2, 2, v78
	v_xor_b32_e32 v2, v2, v79
	v_lshl_add_u32 v71, v2, 4, v0
	v_lshl_add_u32 v75, v2, 4, v1
	v_add_u32_e32 v2, 4, v78
	v_xor_b32_e32 v2, v2, v79
	v_lshl_add_u32 v72, v2, 4, v0
	v_lshl_add_u32 v76, v2, 4, v1
	v_add_u32_e32 v2, 6, v78
	v_xor_b32_e32 v2, v2, v79
	v_lshl_add_u32 v73, v2, 4, v0
	v_lshl_add_u32 v77, v2, 4, v1
	s_lshl_b32 s1, s0, 16
	s_lshl_b32 s0, s0, 12
	s_add_u32 s98, s98, s1
	s_addc_u32 s99, s99, 0
	s_add_u32 s100, s100, s1
	s_addc_u32 s101, s101, 0
	s_waitcnt lgkmcnt(0)
	s_barrier
	s_add_u32 m0, s0, 0x0
	s_nop 0
	global_load_lds_dwordx4 v68, s[98:99]
	s_add_u32 m0, s0, 0x400
	s_add_u32 s14, s98, 0x4000
	s_addc_u32 s15, s99, 0
	global_load_lds_dwordx4 v69, s[14:15]
	s_add_u32 m0, s0, 0x800
	s_add_u32 s14, s98, 0x8000
	s_addc_u32 s15, s99, 0
	global_load_lds_dwordx4 v68, s[14:15]
	s_add_u32 m0, s0, 0xc00
	s_add_u32 s14, s98, 0xc000
	s_addc_u32 s15, s99, 0
	global_load_lds_dwordx4 v69, s[14:15]
	s_add_u32 m0, s0, 0x4000
	s_nop 0
	global_load_lds_dwordx4 v68, s[100:101]
	s_add_u32 m0, s0, 0x4400
	s_add_u32 s14, s100, 0x4000
	s_addc_u32 s15, s101, 0
	global_load_lds_dwordx4 v69, s[14:15]
	s_add_u32 m0, s0, 0x4800
	s_add_u32 s14, s100, 0x8000
	s_addc_u32 s15, s101, 0
	global_load_lds_dwordx4 v68, s[14:15]
	s_add_u32 m0, s0, 0x4c00
	s_add_u32 s14, s100, 0xc000
	s_addc_u32 s15, s101, 0
	global_load_lds_dwordx4 v69, s[14:15]
	s_add_u32 s98, s98, 0x80
	s_addc_u32 s99, s99, 0
	s_add_u32 s100, s100, 0x80
	s_addc_u32 s101, s101, 0
	v_mov_b32_e32 v4, 0
	v_mov_b32_e32 v5, 0
	v_mov_b32_e32 v6, 0
	v_mov_b32_e32 v7, 0
	v_mov_b32_e32 v8, 0
	v_mov_b32_e32 v9, 0
	v_mov_b32_e32 v10, 0
	v_mov_b32_e32 v11, 0
	v_mov_b32_e32 v12, 0
	v_mov_b32_e32 v13, 0
	v_mov_b32_e32 v14, 0
	v_mov_b32_e32 v15, 0
	v_mov_b32_e32 v16, 0
	v_mov_b32_e32 v17, 0
	v_mov_b32_e32 v18, 0
	v_mov_b32_e32 v19, 0
	v_mov_b32_e32 v20, 0
	v_mov_b32_e32 v21, 0
	v_mov_b32_e32 v22, 0
	v_mov_b32_e32 v23, 0
	v_mov_b32_e32 v24, 0
	v_mov_b32_e32 v25, 0
	v_mov_b32_e32 v26, 0
	v_mov_b32_e32 v27, 0
	v_mov_b32_e32 v28, 0
	v_mov_b32_e32 v29, 0
	v_mov_b32_e32 v30, 0
	v_mov_b32_e32 v31, 0
	v_mov_b32_e32 v32, 0
	v_mov_b32_e32 v33, 0
	v_mov_b32_e32 v34, 0
	v_mov_b32_e32 v35, 0
	v_mov_b32_e32 v36, 0
	v_mov_b32_e32 v37, 0
	v_mov_b32_e32 v38, 0
	v_mov_b32_e32 v39, 0
	v_mov_b32_e32 v40, 0
	v_mov_b32_e32 v41, 0
	v_mov_b32_e32 v42, 0
	v_mov_b32_e32 v43, 0
	v_mov_b32_e32 v44, 0
	v_mov_b32_e32 v45, 0
	v_mov_b32_e32 v46, 0
	v_mov_b32_e32 v47, 0
	v_mov_b32_e32 v48, 0
	v_mov_b32_e32 v49, 0
	v_mov_b32_e32 v50, 0
	v_mov_b32_e32 v51, 0
	v_mov_b32_e32 v52, 0
	v_mov_b32_e32 v53, 0
	v_mov_b32_e32 v54, 0
	v_mov_b32_e32 v55, 0
	v_mov_b32_e32 v56, 0
	v_mov_b32_e32 v57, 0
	v_mov_b32_e32 v58, 0
	v_mov_b32_e32 v59, 0
	v_mov_b32_e32 v60, 0
	v_mov_b32_e32 v61, 0
	v_mov_b32_e32 v62, 0
	v_mov_b32_e32 v63, 0
	v_mov_b32_e32 v64, 0
	v_mov_b32_e32 v65, 0
	v_mov_b32_e32 v66, 0
	v_mov_b32_e32 v67, 0
	s_mov_b32 s11, 0
